# branch epilogue gate-tile loads with nt cache hint (read-once / read-twice streaming data)
# baseline (speedup 1.0000x reference)
; __device__ __forceinline__ float bf_lo(unsigned w) { return __uint_as_float(w << 16); }
; __device__ __forceinline__ float bf_hi(unsigned w) { return __uint_as_float(w & 0xffff0000u); }
;     __device__ __forceinline__ void operator()(ACC_T, const Unit& u, int wr, int wc, int fr, int fq) const {
;     ...
;             for (int m = 0; m < 4; ++m) { const size_t row = (size_t)(row0 + ai * HALF + m * 16);
; #pragma unroll
;                 for (int bj = 0; bj < 2; ++bj) {
;                     const u32x4 gw = *(const u32x4*)(Gt + row * GW + u.z * DM + col0 + bj * HALF);
;                     f32x4 v0 = acc[ai][bj][m][0], v1 = acc[ai][bj][m][1];
;                     v0[0] *= bf_lo(gw.x); v0[1] *= bf_hi(gw.x); v0[2] *= bf_lo(gw.y); v0[3] *= bf_hi(gw.y);
;                     v1[0] *= bf_lo(gw.z); v1[1] *= bf_hi(gw.z); v1[2] *= bf_lo(gw.w); v1[3] *= bf_hi(gw.w);
;                     float* mp = M32 + (size_t)u.pm * (SLOTB / 4) + (row - (size_t)u.pm * BM) * DM + col0 + bj * HALF;
;                     if (u.z > 0) { v0 += *(const f32x4*)mp; v1 += *(const f32x4*)(mp + 4); }
;                     if (u.z < 2) { *(f32x4*)mp = v0; *(f32x4*)(mp + 4) = v1; }
.LBB0_667:
	v_readlane_b32 s24, v251, 58
	v_readlane_b32 s25, v251, 59
	v_readlane_b32 s22, v254, 52
	v_readlane_b32 s23, v254, 53
	v_lshl_or_b32 v143, s3, 8, v152
	v_mul_u32_u24_e32 v140, 0x1800, v150
	v_lshlrev_b32_e32 v142, 11, v150
	v_lshl_add_u32 v140, v143, 1, v140
	v_lshl_add_u32 v142, v143, 1, v142
	s_mul_i32 s44, s14, 0x180000
	s_lshl_b32 s45, s2, 11
	s_add_u32 s44, s44, s45
	s_add_u32 s24, s24, s44
	s_addc_u32 s25, s25, 0
	s_lshl_b32 s44, s14, 19
	s_add_u32 s22, s22, s44
	s_addc_u32 s23, s23, 0
	s_cmp_eq_u32 s2, 2
	s_cbranch_scc1 .Lbr_zlast
	global_load_dwordx4 v[144:147], v140, s[24:25] nt
	global_load_dwordx4 v[154:157], v140, s[24:25] offset:2048 nt
	global_load_dwordx4 v[158:161], v140, s[24:25] offset:256 nt
	global_load_dwordx4 v[162:165], v140, s[24:25] offset:2304 nt
	s_add_u32 s24, s24, 0x18000
	s_addc_u32 s25, s25, 0
	global_load_dwordx4 v[166:169], v140, s[24:25] nt
	global_load_dwordx4 v[170:173], v140, s[24:25] offset:2048 nt
	global_load_dwordx4 v[174:177], v140, s[24:25] offset:256 nt
	global_load_dwordx4 v[178:181], v140, s[24:25] offset:2304 nt
	s_add_u32 s24, s24, 0x18000
	s_addc_u32 s25, s25, 0
	global_load_dwordx4 v[182:185], v140, s[24:25] nt
	global_load_dwordx4 v[186:189], v140, s[24:25] offset:2048 nt
	global_load_dwordx4 v[190:193], v140, s[24:25] offset:256 nt
	global_load_dwordx4 v[194:197], v140, s[24:25] offset:2304 nt
	s_add_u32 s24, s24, 0x18000
	s_addc_u32 s25, s25, 0
	global_load_dwordx4 v[198:201], v140, s[24:25] nt
	global_load_dwordx4 v[202:205], v140, s[24:25] offset:2048 nt
	s_waitcnt vmcnt(12)
	v_lshlrev_b32_e32 v148, 16, v144
	v_and_b32_e32 v149, 0xffff0000, v144
	v_lshlrev_b32_e32 v210, 16, v146
	v_and_b32_e32 v211, 0xffff0000, v146
	v_lshlrev_b32_e32 v144, 16, v145
	v_and_b32_e32 v145, 0xffff0000, v145
	v_lshlrev_b32_e32 v146, 16, v147
	v_and_b32_e32 v147, 0xffff0000, v147
	v_lshlrev_b32_e32 v212, 16, v154
	v_and_b32_e32 v213, 0xffff0000, v154
	v_lshlrev_b32_e32 v214, 16, v156
	v_and_b32_e32 v215, 0xffff0000, v156
	v_lshlrev_b32_e32 v154, 16, v155
	v_and_b32_e32 v155, 0xffff0000, v155
	v_lshlrev_b32_e32 v156, 16, v157
	v_and_b32_e32 v157, 0xffff0000, v157
	v_rcp_f32_e32 v212, v212
	v_rcp_f32_e32 v213, v213
	v_rcp_f32_e32 v154, v154
	v_rcp_f32_e32 v155, v155
	v_rcp_f32_e32 v214, v214
	v_rcp_f32_e32 v215, v215
	v_rcp_f32_e32 v156, v156
	v_rcp_f32_e32 v157, v157
	s_nop 0
	v_pk_mul_f32 v[148:149], v[148:149], v[212:213]
	v_pk_mul_f32 v[144:145], v[144:145], v[154:155]
	v_pk_mul_f32 v[210:211], v[210:211], v[214:215]
	v_pk_mul_f32 v[146:147], v[146:147], v[156:157]
	v_pk_mul_f32 v[126:127], v[126:127], v[148:149]
	v_pk_mul_f32 v[128:129], v[128:129], v[144:145]
	v_pk_mul_f32 v[122:123], v[122:123], v[210:211]
	v_pk_mul_f32 v[124:125], v[124:125], v[146:147]
	global_load_dwordx4 v[206:209], v140, s[24:25] offset:256 nt
	global_load_dwordx4 v[144:147], v140, s[24:25] offset:2304 nt
	s_add_u32 s24, s24, 0x78000
	s_addc_u32 s25, s25, 0
	s_waitcnt vmcnt(12)
	v_lshlrev_b32_e32 v148, 16, v158
	v_and_b32_e32 v149, 0xffff0000, v158
	v_lshlrev_b32_e32 v210, 16, v160
	v_and_b32_e32 v211, 0xffff0000, v160
	v_lshlrev_b32_e32 v158, 16, v159
	v_and_b32_e32 v159, 0xffff0000, v159
	v_lshlrev_b32_e32 v160, 16, v161
	v_and_b32_e32 v161, 0xffff0000, v161
	v_lshlrev_b32_e32 v212, 16, v162
	v_and_b32_e32 v213, 0xffff0000, v162
	v_lshlrev_b32_e32 v214, 16, v164
	v_and_b32_e32 v215, 0xffff0000, v164
	v_lshlrev_b32_e32 v162, 16, v163
	v_and_b32_e32 v163, 0xffff0000, v163
	v_lshlrev_b32_e32 v164, 16, v165
	v_and_b32_e32 v165, 0xffff0000, v165
	v_rcp_f32_e32 v212, v212
	v_rcp_f32_e32 v213, v213
	v_rcp_f32_e32 v162, v162
	v_rcp_f32_e32 v163, v163
	v_rcp_f32_e32 v214, v214
	v_rcp_f32_e32 v215, v215
	v_rcp_f32_e32 v164, v164
	v_rcp_f32_e32 v165, v165
	s_nop 0
	v_pk_mul_f32 v[148:149], v[148:149], v[212:213]
	v_pk_mul_f32 v[158:159], v[158:159], v[162:163]
	v_pk_mul_f32 v[210:211], v[210:211], v[214:215]
	v_pk_mul_f32 v[160:161], v[160:161], v[164:165]
	v_pk_mul_f32 v[118:119], v[118:119], v[148:149]
	v_pk_mul_f32 v[120:121], v[120:121], v[158:159]
	v_pk_mul_f32 v[114:115], v[114:115], v[210:211]
	v_pk_mul_f32 v[116:117], v[116:117], v[160:161]
	global_load_dwordx4 v[154:157], v140, s[24:25] nt
	global_load_dwordx4 v[158:161], v140, s[24:25] offset:2048 nt
	s_waitcnt vmcnt(12)
	v_lshlrev_b32_e32 v148, 16, v166
	v_and_b32_e32 v149, 0xffff0000, v166
	v_lshlrev_b32_e32 v210, 16, v168
	v_and_b32_e32 v211, 0xffff0000, v168
	v_lshlrev_b32_e32 v166, 16, v167
	v_and_b32_e32 v167, 0xffff0000, v167
	v_lshlrev_b32_e32 v168, 16, v169
	v_and_b32_e32 v169, 0xffff0000, v169
	v_lshlrev_b32_e32 v212, 16, v170
	v_and_b32_e32 v213, 0xffff0000, v170
	v_lshlrev_b32_e32 v214, 16, v172
	v_and_b32_e32 v215, 0xffff0000, v172
	v_lshlrev_b32_e32 v170, 16, v171
	v_and_b32_e32 v171, 0xffff0000, v171
	v_lshlrev_b32_e32 v172, 16, v173
	v_and_b32_e32 v173, 0xffff0000, v173
	v_rcp_f32_e32 v212, v212
	v_rcp_f32_e32 v213, v213
	v_rcp_f32_e32 v170, v170
	v_rcp_f32_e32 v171, v171
	v_rcp_f32_e32 v214, v214
	v_rcp_f32_e32 v215, v215
	v_rcp_f32_e32 v172, v172
	v_rcp_f32_e32 v173, v173
	s_nop 0
	v_pk_mul_f32 v[148:149], v[148:149], v[212:213]
	v_pk_mul_f32 v[166:167], v[166:167], v[170:171]
	v_pk_mul_f32 v[210:211], v[210:211], v[214:215]
	v_pk_mul_f32 v[168:169], v[168:169], v[172:173]
	v_pk_mul_f32 v[110:111], v[110:111], v[148:149]
	v_pk_mul_f32 v[112:113], v[112:113], v[166:167]
	v_pk_mul_f32 v[106:107], v[106:107], v[210:211]
	v_pk_mul_f32 v[108:109], v[108:109], v[168:169]
	global_load_dwordx4 v[162:165], v140, s[24:25] offset:256 nt
	global_load_dwordx4 v[166:169], v140, s[24:25] offset:2304 nt
	s_add_u32 s24, s24, 0x18000
	s_addc_u32 s25, s25, 0
	s_waitcnt vmcnt(12)
; __device__ __forceinline__ float bf_lo(unsigned w) { return __uint_as_float(w << 16); }
; __device__ __forceinline__ float bf_hi(unsigned w) { return __uint_as_float(w & 0xffff0000u); }
;     __device__ __forceinline__ void operator()(ACC_T, const Unit& u, int wr, int wc, int fr, int fq) const {
;     ...
;             for (int m = 0; m < 4; ++m) { const size_t row = (size_t)(row0 + ai * HALF + m * 16);
; #pragma unroll
;                 for (int bj = 0; bj < 2; ++bj) {
;                     const u32x4 gw = *(const u32x4*)(Gt + row * GW + u.z * DM + col0 + bj * HALF);
;                     f32x4 v0 = acc[ai][bj][m][0], v1 = acc[ai][bj][m][1];
;                     v0[0] *= bf_lo(gw.x); v0[1] *= bf_hi(gw.x); v0[2] *= bf_lo(gw.y); v0[3] *= bf_hi(gw.y);
;                     v1[0] *= bf_lo(gw.z); v1[1] *= bf_hi(gw.z); v1[2] *= bf_lo(gw.w); v1[3] *= bf_hi(gw.w);
;                     float* mp = M32 + (size_t)u.pm * (SLOTB / 4) + (row - (size_t)u.pm * BM) * DM + col0 + bj * HALF;
;                     if (u.z > 0) { v0 += *(const f32x4*)mp; v1 += *(const f32x4*)(mp + 4); }
;                     if (u.z < 2) { *(f32x4*)mp = v0; *(f32x4*)(mp + 4) = v1; }
	v_lshlrev_b32_e32 v148, 16, v174
	v_and_b32_e32 v149, 0xffff0000, v174
	v_lshlrev_b32_e32 v210, 16, v176
	v_and_b32_e32 v211, 0xffff0000, v176
	v_lshlrev_b32_e32 v174, 16, v175
	v_and_b32_e32 v175, 0xffff0000, v175
	v_lshlrev_b32_e32 v176, 16, v177
	v_and_b32_e32 v177, 0xffff0000, v177
	v_lshlrev_b32_e32 v212, 16, v178
	v_and_b32_e32 v213, 0xffff0000, v178
	v_lshlrev_b32_e32 v214, 16, v180
	v_and_b32_e32 v215, 0xffff0000, v180
	v_lshlrev_b32_e32 v178, 16, v179
	v_and_b32_e32 v179, 0xffff0000, v179
	v_lshlrev_b32_e32 v180, 16, v181
	v_and_b32_e32 v181, 0xffff0000, v181
	v_rcp_f32_e32 v212, v212
	v_rcp_f32_e32 v213, v213
	v_rcp_f32_e32 v178, v178
	v_rcp_f32_e32 v179, v179
	v_rcp_f32_e32 v214, v214
	v_rcp_f32_e32 v215, v215
	v_rcp_f32_e32 v180, v180
	v_rcp_f32_e32 v181, v181
	s_nop 0
	v_pk_mul_f32 v[148:149], v[148:149], v[212:213]
	v_pk_mul_f32 v[174:175], v[174:175], v[178:179]
	v_pk_mul_f32 v[210:211], v[210:211], v[214:215]
	v_pk_mul_f32 v[176:177], v[176:177], v[180:181]
	v_pk_mul_f32 v[102:103], v[102:103], v[148:149]
	v_pk_mul_f32 v[104:105], v[104:105], v[174:175]
	v_pk_mul_f32 v[98:99], v[98:99], v[210:211]
	v_pk_mul_f32 v[100:101], v[100:101], v[176:177]
	global_load_dwordx4 v[170:173], v140, s[24:25] nt
	global_load_dwordx4 v[174:177], v140, s[24:25] offset:2048 nt
	s_waitcnt vmcnt(12)
	v_lshlrev_b32_e32 v148, 16, v182
	v_and_b32_e32 v149, 0xffff0000, v182
	v_lshlrev_b32_e32 v210, 16, v184
	v_and_b32_e32 v211, 0xffff0000, v184
	v_lshlrev_b32_e32 v182, 16, v183
	v_and_b32_e32 v183, 0xffff0000, v183
	v_lshlrev_b32_e32 v184, 16, v185
	v_and_b32_e32 v185, 0xffff0000, v185
	v_lshlrev_b32_e32 v212, 16, v186
	v_and_b32_e32 v213, 0xffff0000, v186
	v_lshlrev_b32_e32 v214, 16, v188
	v_and_b32_e32 v215, 0xffff0000, v188
	v_lshlrev_b32_e32 v186, 16, v187
	v_and_b32_e32 v187, 0xffff0000, v187
	v_lshlrev_b32_e32 v188, 16, v189
	v_and_b32_e32 v189, 0xffff0000, v189
	v_rcp_f32_e32 v212, v212
	v_rcp_f32_e32 v213, v213
	v_rcp_f32_e32 v186, v186
	v_rcp_f32_e32 v187, v187
	v_rcp_f32_e32 v214, v214
	v_rcp_f32_e32 v215, v215
	v_rcp_f32_e32 v188, v188
	v_rcp_f32_e32 v189, v189
	s_nop 0
	v_pk_mul_f32 v[148:149], v[148:149], v[212:213]
	v_pk_mul_f32 v[182:183], v[182:183], v[186:187]
	v_pk_mul_f32 v[210:211], v[210:211], v[214:215]
	v_pk_mul_f32 v[184:185], v[184:185], v[188:189]
	v_pk_mul_f32 v[94:95], v[94:95], v[148:149]
	v_pk_mul_f32 v[96:97], v[96:97], v[182:183]
	v_pk_mul_f32 v[90:91], v[90:91], v[210:211]
	v_pk_mul_f32 v[92:93], v[92:93], v[184:185]
	global_load_dwordx4 v[178:181], v140, s[24:25] offset:256 nt
	global_load_dwordx4 v[182:185], v140, s[24:25] offset:2304 nt
	s_add_u32 s24, s24, 0x18000
	s_addc_u32 s25, s25, 0
	s_waitcnt vmcnt(12)
	v_lshlrev_b32_e32 v148, 16, v190
	v_and_b32_e32 v149, 0xffff0000, v190
	v_lshlrev_b32_e32 v210, 16, v192
	v_and_b32_e32 v211, 0xffff0000, v192
	v_lshlrev_b32_e32 v190, 16, v191
	v_and_b32_e32 v191, 0xffff0000, v191
	v_lshlrev_b32_e32 v192, 16, v193
	v_and_b32_e32 v193, 0xffff0000, v193
	v_lshlrev_b32_e32 v212, 16, v194
	v_and_b32_e32 v213, 0xffff0000, v194
	v_lshlrev_b32_e32 v214, 16, v196
	v_and_b32_e32 v215, 0xffff0000, v196
	v_lshlrev_b32_e32 v194, 16, v195
	v_and_b32_e32 v195, 0xffff0000, v195
	v_lshlrev_b32_e32 v196, 16, v197
	v_and_b32_e32 v197, 0xffff0000, v197
	v_rcp_f32_e32 v212, v212
	v_rcp_f32_e32 v213, v213
	v_rcp_f32_e32 v194, v194
	v_rcp_f32_e32 v195, v195
	v_rcp_f32_e32 v214, v214
	v_rcp_f32_e32 v215, v215
	v_rcp_f32_e32 v196, v196
	v_rcp_f32_e32 v197, v197
	s_nop 0
	v_pk_mul_f32 v[148:149], v[148:149], v[212:213]
	v_pk_mul_f32 v[190:191], v[190:191], v[194:195]
	v_pk_mul_f32 v[210:211], v[210:211], v[214:215]
	v_pk_mul_f32 v[192:193], v[192:193], v[196:197]
	v_pk_mul_f32 v[86:87], v[86:87], v[148:149]
	v_pk_mul_f32 v[88:89], v[88:89], v[190:191]
	v_pk_mul_f32 v[82:83], v[82:83], v[210:211]
	v_pk_mul_f32 v[84:85], v[84:85], v[192:193]
	global_load_dwordx4 v[186:189], v140, s[24:25] nt
	global_load_dwordx4 v[190:193], v140, s[24:25] offset:2048 nt
	s_waitcnt vmcnt(12)
	v_lshlrev_b32_e32 v148, 16, v198
	v_and_b32_e32 v149, 0xffff0000, v198
	v_lshlrev_b32_e32 v210, 16, v200
	v_and_b32_e32 v211, 0xffff0000, v200
	v_lshlrev_b32_e32 v198, 16, v199
	v_and_b32_e32 v199, 0xffff0000, v199
	v_lshlrev_b32_e32 v200, 16, v201
	v_and_b32_e32 v201, 0xffff0000, v201
	v_lshlrev_b32_e32 v212, 16, v202
	v_and_b32_e32 v213, 0xffff0000, v202
	v_lshlrev_b32_e32 v214, 16, v204
	v_and_b32_e32 v215, 0xffff0000, v204
	v_lshlrev_b32_e32 v202, 16, v203
	v_and_b32_e32 v203, 0xffff0000, v203
	v_lshlrev_b32_e32 v204, 16, v205
	v_and_b32_e32 v205, 0xffff0000, v205
	v_rcp_f32_e32 v212, v212
	v_rcp_f32_e32 v213, v213
	v_rcp_f32_e32 v202, v202
	v_rcp_f32_e32 v203, v203
	v_rcp_f32_e32 v214, v214
	v_rcp_f32_e32 v215, v215
	v_rcp_f32_e32 v204, v204
	v_rcp_f32_e32 v205, v205
	s_nop 0
	v_pk_mul_f32 v[148:149], v[148:149], v[212:213]
	v_pk_mul_f32 v[198:199], v[198:199], v[202:203]
	v_pk_mul_f32 v[210:211], v[210:211], v[214:215]
	v_pk_mul_f32 v[200:201], v[200:201], v[204:205]
	v_pk_mul_f32 v[78:79], v[78:79], v[148:149]
	v_pk_mul_f32 v[80:81], v[80:81], v[198:199]
	v_pk_mul_f32 v[74:75], v[74:75], v[210:211]
	v_pk_mul_f32 v[76:77], v[76:77], v[200:201]
	global_load_dwordx4 v[194:197], v140, s[24:25] offset:256 nt
	global_load_dwordx4 v[198:201], v140, s[24:25] offset:2304 nt
	s_add_u32 s24, s24, 0x18000
	s_addc_u32 s25, s25, 0
	s_waitcnt vmcnt(12)
; __device__ __forceinline__ float bf_lo(unsigned w) { return __uint_as_float(w << 16); }
; __device__ __forceinline__ float bf_hi(unsigned w) { return __uint_as_float(w & 0xffff0000u); }
;     __device__ __forceinline__ void operator()(ACC_T, const Unit& u, int wr, int wc, int fr, int fq) const {
;     ...
;             for (int m = 0; m < 4; ++m) { const size_t row = (size_t)(row0 + ai * HALF + m * 16);
; #pragma unroll
;                 for (int bj = 0; bj < 2; ++bj) {
;                     const u32x4 gw = *(const u32x4*)(Gt + row * GW + u.z * DM + col0 + bj * HALF);
;                     f32x4 v0 = acc[ai][bj][m][0], v1 = acc[ai][bj][m][1];
;                     v0[0] *= bf_lo(gw.x); v0[1] *= bf_hi(gw.x); v0[2] *= bf_lo(gw.y); v0[3] *= bf_hi(gw.y);
;                     v1[0] *= bf_lo(gw.z); v1[1] *= bf_hi(gw.z); v1[2] *= bf_lo(gw.w); v1[3] *= bf_hi(gw.w);
;                     float* mp = M32 + (size_t)u.pm * (SLOTB / 4) + (row - (size_t)u.pm * BM) * DM + col0 + bj * HALF;
;                     if (u.z > 0) { v0 += *(const f32x4*)mp; v1 += *(const f32x4*)(mp + 4); }
;                     if (u.z < 2) { *(f32x4*)mp = v0; *(f32x4*)(mp + 4) = v1; }
	v_lshlrev_b32_e32 v148, 16, v206
	v_and_b32_e32 v149, 0xffff0000, v206
	v_lshlrev_b32_e32 v210, 16, v208
	v_and_b32_e32 v211, 0xffff0000, v208
	v_lshlrev_b32_e32 v206, 16, v207
	v_and_b32_e32 v207, 0xffff0000, v207
	v_lshlrev_b32_e32 v208, 16, v209
	v_and_b32_e32 v209, 0xffff0000, v209
	v_lshlrev_b32_e32 v212, 16, v144
	v_and_b32_e32 v213, 0xffff0000, v144
	v_lshlrev_b32_e32 v214, 16, v146
	v_and_b32_e32 v215, 0xffff0000, v146
	v_lshlrev_b32_e32 v144, 16, v145
	v_and_b32_e32 v145, 0xffff0000, v145
	v_lshlrev_b32_e32 v146, 16, v147
	v_and_b32_e32 v147, 0xffff0000, v147
	v_rcp_f32_e32 v212, v212
	v_rcp_f32_e32 v213, v213
	v_rcp_f32_e32 v144, v144
	v_rcp_f32_e32 v145, v145
	v_rcp_f32_e32 v214, v214
	v_rcp_f32_e32 v215, v215
	v_rcp_f32_e32 v146, v146
	v_rcp_f32_e32 v147, v147
	s_nop 0
	v_pk_mul_f32 v[148:149], v[148:149], v[212:213]
	v_pk_mul_f32 v[206:207], v[206:207], v[144:145]
	v_pk_mul_f32 v[210:211], v[210:211], v[214:215]
	v_pk_mul_f32 v[208:209], v[208:209], v[146:147]
	v_pk_mul_f32 v[70:71], v[70:71], v[148:149]
	v_pk_mul_f32 v[72:73], v[72:73], v[206:207]
	v_pk_mul_f32 v[66:67], v[66:67], v[210:211]
	v_pk_mul_f32 v[68:69], v[68:69], v[208:209]
	global_load_dwordx4 v[202:205], v140, s[24:25] nt
	global_load_dwordx4 v[206:209], v140, s[24:25] offset:2048 nt
	s_waitcnt vmcnt(12)
	v_lshlrev_b32_e32 v148, 16, v154
	v_and_b32_e32 v149, 0xffff0000, v154
	v_lshlrev_b32_e32 v210, 16, v156
	v_and_b32_e32 v211, 0xffff0000, v156
	v_lshlrev_b32_e32 v154, 16, v155
	v_and_b32_e32 v155, 0xffff0000, v155
	v_lshlrev_b32_e32 v156, 16, v157
	v_and_b32_e32 v157, 0xffff0000, v157
	v_lshlrev_b32_e32 v212, 16, v158
	v_and_b32_e32 v213, 0xffff0000, v158
	v_lshlrev_b32_e32 v214, 16, v160
	v_and_b32_e32 v215, 0xffff0000, v160
	v_lshlrev_b32_e32 v158, 16, v159
	v_and_b32_e32 v159, 0xffff0000, v159
	v_lshlrev_b32_e32 v160, 16, v161
	v_and_b32_e32 v161, 0xffff0000, v161
	v_rcp_f32_e32 v212, v212
	v_rcp_f32_e32 v213, v213
	v_rcp_f32_e32 v158, v158
	v_rcp_f32_e32 v159, v159
	v_rcp_f32_e32 v214, v214
	v_rcp_f32_e32 v215, v215
	v_rcp_f32_e32 v160, v160
	v_rcp_f32_e32 v161, v161
	s_nop 0
	v_pk_mul_f32 v[148:149], v[148:149], v[212:213]
	v_pk_mul_f32 v[154:155], v[154:155], v[158:159]
	v_pk_mul_f32 v[210:211], v[210:211], v[214:215]
	v_pk_mul_f32 v[156:157], v[156:157], v[160:161]
	v_pk_mul_f32 v[62:63], v[62:63], v[148:149]
	v_pk_mul_f32 v[64:65], v[64:65], v[154:155]
	v_pk_mul_f32 v[58:59], v[58:59], v[210:211]
	v_pk_mul_f32 v[60:61], v[60:61], v[156:157]
	global_load_dwordx4 v[144:147], v140, s[24:25] offset:256 nt
	global_load_dwordx4 v[154:157], v140, s[24:25] offset:2304 nt
	s_waitcnt vmcnt(12)
	v_lshlrev_b32_e32 v148, 16, v162
	v_and_b32_e32 v149, 0xffff0000, v162
	v_lshlrev_b32_e32 v210, 16, v164
	v_and_b32_e32 v211, 0xffff0000, v164
	v_lshlrev_b32_e32 v162, 16, v163
	v_and_b32_e32 v163, 0xffff0000, v163
	v_lshlrev_b32_e32 v164, 16, v165
	v_and_b32_e32 v165, 0xffff0000, v165
	v_lshlrev_b32_e32 v212, 16, v166
	v_and_b32_e32 v213, 0xffff0000, v166
	v_lshlrev_b32_e32 v214, 16, v168
	v_and_b32_e32 v215, 0xffff0000, v168
	v_lshlrev_b32_e32 v166, 16, v167
	v_and_b32_e32 v167, 0xffff0000, v167
	v_lshlrev_b32_e32 v168, 16, v169
	v_and_b32_e32 v169, 0xffff0000, v169
	v_rcp_f32_e32 v212, v212
	v_rcp_f32_e32 v213, v213
	v_rcp_f32_e32 v166, v166
	v_rcp_f32_e32 v167, v167
	v_rcp_f32_e32 v214, v214
	v_rcp_f32_e32 v215, v215
	v_rcp_f32_e32 v168, v168
	v_rcp_f32_e32 v169, v169
	s_nop 0
	v_pk_mul_f32 v[148:149], v[148:149], v[212:213]
	v_pk_mul_f32 v[162:163], v[162:163], v[166:167]
	v_pk_mul_f32 v[210:211], v[210:211], v[214:215]
	v_pk_mul_f32 v[164:165], v[164:165], v[168:169]
	v_pk_mul_f32 v[54:55], v[54:55], v[148:149]
	v_pk_mul_f32 v[56:57], v[56:57], v[162:163]
	v_pk_mul_f32 v[50:51], v[50:51], v[210:211]
	v_pk_mul_f32 v[52:53], v[52:53], v[164:165]
	s_waitcnt vmcnt(10)
	v_lshlrev_b32_e32 v148, 16, v170
	v_and_b32_e32 v149, 0xffff0000, v170
	v_lshlrev_b32_e32 v210, 16, v172
	v_and_b32_e32 v211, 0xffff0000, v172
	v_lshlrev_b32_e32 v170, 16, v171
	v_and_b32_e32 v171, 0xffff0000, v171
	v_lshlrev_b32_e32 v172, 16, v173
	v_and_b32_e32 v173, 0xffff0000, v173
	v_lshlrev_b32_e32 v212, 16, v174
	v_and_b32_e32 v213, 0xffff0000, v174
	v_lshlrev_b32_e32 v214, 16, v176
	v_and_b32_e32 v215, 0xffff0000, v176
	v_lshlrev_b32_e32 v174, 16, v175
	v_and_b32_e32 v175, 0xffff0000, v175
	v_lshlrev_b32_e32 v176, 16, v177
	v_and_b32_e32 v177, 0xffff0000, v177
	v_rcp_f32_e32 v212, v212
	v_rcp_f32_e32 v213, v213
	v_rcp_f32_e32 v174, v174
	v_rcp_f32_e32 v175, v175
	v_rcp_f32_e32 v214, v214
	v_rcp_f32_e32 v215, v215
	v_rcp_f32_e32 v176, v176
	v_rcp_f32_e32 v177, v177
	s_nop 0
	v_pk_mul_f32 v[148:149], v[148:149], v[212:213]
	v_pk_mul_f32 v[170:171], v[170:171], v[174:175]
	v_pk_mul_f32 v[210:211], v[210:211], v[214:215]
	v_pk_mul_f32 v[172:173], v[172:173], v[176:177]
	v_pk_mul_f32 v[46:47], v[46:47], v[148:149]
	v_pk_mul_f32 v[48:49], v[48:49], v[170:171]
	v_pk_mul_f32 v[42:43], v[42:43], v[210:211]
	v_pk_mul_f32 v[44:45], v[44:45], v[172:173]
	s_waitcnt vmcnt(8)
	v_lshlrev_b32_e32 v148, 16, v178
	v_and_b32_e32 v149, 0xffff0000, v178
	v_lshlrev_b32_e32 v210, 16, v180
	v_and_b32_e32 v211, 0xffff0000, v180
	v_lshlrev_b32_e32 v178, 16, v179
	v_and_b32_e32 v179, 0xffff0000, v179
	v_lshlrev_b32_e32 v180, 16, v181
	v_and_b32_e32 v181, 0xffff0000, v181
	v_lshlrev_b32_e32 v212, 16, v182
	v_and_b32_e32 v213, 0xffff0000, v182
	v_lshlrev_b32_e32 v214, 16, v184
	v_and_b32_e32 v215, 0xffff0000, v184
	v_lshlrev_b32_e32 v182, 16, v183
	v_and_b32_e32 v183, 0xffff0000, v183
	v_lshlrev_b32_e32 v184, 16, v185
	v_and_b32_e32 v185, 0xffff0000, v185
	v_rcp_f32_e32 v212, v212
	v_rcp_f32_e32 v213, v213
	v_rcp_f32_e32 v182, v182
	v_rcp_f32_e32 v183, v183
	v_rcp_f32_e32 v214, v214
	v_rcp_f32_e32 v215, v215
	v_rcp_f32_e32 v184, v184
	v_rcp_f32_e32 v185, v185
	s_nop 0
	v_pk_mul_f32 v[148:149], v[148:149], v[212:213]
	v_pk_mul_f32 v[178:179], v[178:179], v[182:183]
	v_pk_mul_f32 v[210:211], v[210:211], v[214:215]
	v_pk_mul_f32 v[180:181], v[180:181], v[184:185]
	v_pk_mul_f32 v[38:39], v[38:39], v[148:149]
	v_pk_mul_f32 v[40:41], v[40:41], v[178:179]
	v_pk_mul_f32 v[34:35], v[34:35], v[210:211]
	v_pk_mul_f32 v[36:37], v[36:37], v[180:181]
	s_waitcnt vmcnt(6)
; __device__ __forceinline__ float bf_lo(unsigned w) { return __uint_as_float(w << 16); }
; __device__ __forceinline__ float bf_hi(unsigned w) { return __uint_as_float(w & 0xffff0000u); }
;     __device__ __forceinline__ void operator()(ACC_T, const Unit& u, int wr, int wc, int fr, int fq) const {
;     ...
;             for (int m = 0; m < 4; ++m) { const size_t row = (size_t)(row0 + ai * HALF + m * 16);
; #pragma unroll
;                 for (int bj = 0; bj < 2; ++bj) {
;                     const u32x4 gw = *(const u32x4*)(Gt + row * GW + u.z * DM + col0 + bj * HALF);
;                     f32x4 v0 = acc[ai][bj][m][0], v1 = acc[ai][bj][m][1];
;                     v0[0] *= bf_lo(gw.x); v0[1] *= bf_hi(gw.x); v0[2] *= bf_lo(gw.y); v0[3] *= bf_hi(gw.y);
;                     v1[0] *= bf_lo(gw.z); v1[1] *= bf_hi(gw.z); v1[2] *= bf_lo(gw.w); v1[3] *= bf_hi(gw.w);
;                     float* mp = M32 + (size_t)u.pm * (SLOTB / 4) + (row - (size_t)u.pm * BM) * DM + col0 + bj * HALF;
;                     if (u.z > 0) { v0 += *(const f32x4*)mp; v1 += *(const f32x4*)(mp + 4); }
;                     if (u.z < 2) { *(f32x4*)mp = v0; *(f32x4*)(mp + 4) = v1; }
	v_lshlrev_b32_e32 v148, 16, v186
	v_and_b32_e32 v149, 0xffff0000, v186
	v_lshlrev_b32_e32 v210, 16, v188
	v_and_b32_e32 v211, 0xffff0000, v188
	v_lshlrev_b32_e32 v186, 16, v187
	v_and_b32_e32 v187, 0xffff0000, v187
	v_lshlrev_b32_e32 v188, 16, v189
	v_and_b32_e32 v189, 0xffff0000, v189
	v_lshlrev_b32_e32 v212, 16, v190
	v_and_b32_e32 v213, 0xffff0000, v190
	v_lshlrev_b32_e32 v214, 16, v192
	v_and_b32_e32 v215, 0xffff0000, v192
	v_lshlrev_b32_e32 v190, 16, v191
	v_and_b32_e32 v191, 0xffff0000, v191
	v_lshlrev_b32_e32 v192, 16, v193
	v_and_b32_e32 v193, 0xffff0000, v193
	v_rcp_f32_e32 v212, v212
	v_rcp_f32_e32 v213, v213
	v_rcp_f32_e32 v190, v190
	v_rcp_f32_e32 v191, v191
	v_rcp_f32_e32 v214, v214
	v_rcp_f32_e32 v215, v215
	v_rcp_f32_e32 v192, v192
	v_rcp_f32_e32 v193, v193
	s_nop 0
	v_pk_mul_f32 v[148:149], v[148:149], v[212:213]
	v_pk_mul_f32 v[186:187], v[186:187], v[190:191]
	v_pk_mul_f32 v[210:211], v[210:211], v[214:215]
	v_pk_mul_f32 v[188:189], v[188:189], v[192:193]
	v_pk_mul_f32 v[30:31], v[30:31], v[148:149]
	v_pk_mul_f32 v[32:33], v[32:33], v[186:187]
	v_pk_mul_f32 v[26:27], v[26:27], v[210:211]
	v_pk_mul_f32 v[28:29], v[28:29], v[188:189]
	s_waitcnt vmcnt(4)
	v_lshlrev_b32_e32 v148, 16, v194
	v_and_b32_e32 v149, 0xffff0000, v194
	v_lshlrev_b32_e32 v210, 16, v196
	v_and_b32_e32 v211, 0xffff0000, v196
	v_lshlrev_b32_e32 v194, 16, v195
	v_and_b32_e32 v195, 0xffff0000, v195
	v_lshlrev_b32_e32 v196, 16, v197
	v_and_b32_e32 v197, 0xffff0000, v197
	v_lshlrev_b32_e32 v212, 16, v198
	v_and_b32_e32 v213, 0xffff0000, v198
	v_lshlrev_b32_e32 v214, 16, v200
	v_and_b32_e32 v215, 0xffff0000, v200
	v_lshlrev_b32_e32 v198, 16, v199
	v_and_b32_e32 v199, 0xffff0000, v199
	v_lshlrev_b32_e32 v200, 16, v201
	v_and_b32_e32 v201, 0xffff0000, v201
	v_rcp_f32_e32 v212, v212
	v_rcp_f32_e32 v213, v213
	v_rcp_f32_e32 v198, v198
	v_rcp_f32_e32 v199, v199
	v_rcp_f32_e32 v214, v214
	v_rcp_f32_e32 v215, v215
	v_rcp_f32_e32 v200, v200
	v_rcp_f32_e32 v201, v201
	s_nop 0
	v_pk_mul_f32 v[148:149], v[148:149], v[212:213]
	v_pk_mul_f32 v[194:195], v[194:195], v[198:199]
	v_pk_mul_f32 v[210:211], v[210:211], v[214:215]
	v_pk_mul_f32 v[196:197], v[196:197], v[200:201]
	v_pk_mul_f32 v[22:23], v[22:23], v[148:149]
	v_pk_mul_f32 v[24:25], v[24:25], v[194:195]
	v_pk_mul_f32 v[18:19], v[18:19], v[210:211]
	v_pk_mul_f32 v[20:21], v[20:21], v[196:197]
	s_waitcnt vmcnt(2)
	v_lshlrev_b32_e32 v148, 16, v202
	v_and_b32_e32 v149, 0xffff0000, v202
	v_lshlrev_b32_e32 v210, 16, v204
	v_and_b32_e32 v211, 0xffff0000, v204
	v_lshlrev_b32_e32 v202, 16, v203
	v_and_b32_e32 v203, 0xffff0000, v203
	v_lshlrev_b32_e32 v204, 16, v205
	v_and_b32_e32 v205, 0xffff0000, v205
	v_lshlrev_b32_e32 v212, 16, v206
	v_and_b32_e32 v213, 0xffff0000, v206
	v_lshlrev_b32_e32 v214, 16, v208
	v_and_b32_e32 v215, 0xffff0000, v208
	v_lshlrev_b32_e32 v206, 16, v207
	v_and_b32_e32 v207, 0xffff0000, v207
	v_lshlrev_b32_e32 v208, 16, v209
	v_and_b32_e32 v209, 0xffff0000, v209
	v_rcp_f32_e32 v212, v212
	v_rcp_f32_e32 v213, v213
	v_rcp_f32_e32 v206, v206
	v_rcp_f32_e32 v207, v207
	v_rcp_f32_e32 v214, v214
	v_rcp_f32_e32 v215, v215
	v_rcp_f32_e32 v208, v208
	v_rcp_f32_e32 v209, v209
	s_nop 0
	v_pk_mul_f32 v[148:149], v[148:149], v[212:213]
	v_pk_mul_f32 v[202:203], v[202:203], v[206:207]
	v_pk_mul_f32 v[210:211], v[210:211], v[214:215]
	v_pk_mul_f32 v[204:205], v[204:205], v[208:209]
	v_pk_mul_f32 v[14:15], v[14:15], v[148:149]
	v_pk_mul_f32 v[16:17], v[16:17], v[202:203]
	v_pk_mul_f32 v[10:11], v[10:11], v[210:211]
	v_pk_mul_f32 v[12:13], v[12:13], v[204:205]
	s_waitcnt vmcnt(0)
	v_lshlrev_b32_e32 v148, 16, v144
	v_and_b32_e32 v149, 0xffff0000, v144
	v_lshlrev_b32_e32 v210, 16, v146
	v_and_b32_e32 v211, 0xffff0000, v146
	v_lshlrev_b32_e32 v144, 16, v145
	v_and_b32_e32 v145, 0xffff0000, v145
	v_lshlrev_b32_e32 v146, 16, v147
	v_and_b32_e32 v147, 0xffff0000, v147
	v_lshlrev_b32_e32 v212, 16, v154
	v_and_b32_e32 v213, 0xffff0000, v154
	v_lshlrev_b32_e32 v214, 16, v156
	v_and_b32_e32 v215, 0xffff0000, v156
	v_lshlrev_b32_e32 v154, 16, v155
	v_and_b32_e32 v155, 0xffff0000, v155
	v_lshlrev_b32_e32 v156, 16, v157
	v_and_b32_e32 v157, 0xffff0000, v157
	v_rcp_f32_e32 v212, v212
	v_rcp_f32_e32 v213, v213
	v_rcp_f32_e32 v154, v154
	v_rcp_f32_e32 v155, v155
	v_rcp_f32_e32 v214, v214
	v_rcp_f32_e32 v215, v215
	v_rcp_f32_e32 v156, v156
	v_rcp_f32_e32 v157, v157
	s_nop 0
	v_pk_mul_f32 v[148:149], v[148:149], v[212:213]
	v_pk_mul_f32 v[144:145], v[144:145], v[154:155]
	v_pk_mul_f32 v[210:211], v[210:211], v[214:215]
	v_pk_mul_f32 v[146:147], v[146:147], v[156:157]
	v_pk_mul_f32 v[6:7], v[6:7], v[148:149]
	v_pk_mul_f32 v[8:9], v[8:9], v[144:145]
	v_pk_mul_f32 v[2:3], v[2:3], v[210:211]
	v_pk_mul_f32 v[4:5], v[4:5], v[146:147]
	s_branch .Lbr_done
; __device__ __forceinline__ unsigned cvt_pk_bf16(float lo, float hi) { f32x2 v = {lo, hi}; bf16x2_t b = __builtin_convertvector(v, bf16x2_t); return __builtin_bit_cast(unsigned, b); }
; __device__ __forceinline__ float bf_lo(unsigned w) { return __uint_as_float(w << 16); }
; __device__ __forceinline__ float bf_hi(unsigned w) { return __uint_as_float(w & 0xffff0000u); }
;     __device__ __forceinline__ void operator()(ACC_T, const Unit& u, int wr, int wc, int fr, int fq) const {
;     ...
;             for (int m = 0; m < 4; ++m) { const size_t row = (size_t)(row0 + ai * HALF + m * 16);
; #pragma unroll
;                 for (int bj = 0; bj < 2; ++bj) {
;                     const u32x4 gw = *(const u32x4*)(Gt + row * GW + u.z * DM + col0 + bj * HALF);
;                     f32x4 v0 = acc[ai][bj][m][0], v1 = acc[ai][bj][m][1];
;                     v0[0] *= bf_lo(gw.x); v0[1] *= bf_hi(gw.x); v0[2] *= bf_lo(gw.y); v0[3] *= bf_hi(gw.y);
;                     v1[0] *= bf_lo(gw.z); v1[1] *= bf_hi(gw.z); v1[2] *= bf_lo(gw.w); v1[3] *= bf_hi(gw.w);
;                     float* mp = M32 + (size_t)u.pm * (SLOTB / 4) + (row - (size_t)u.pm * BM) * DM + col0 + bj * HALF;
;                     if (u.z > 0) { v0 += *(const f32x4*)mp; v1 += *(const f32x4*)(mp + 4); }
;                     if (u.z < 2) { *(f32x4*)mp = v0; *(f32x4*)(mp + 4) = v1; }
;                     else { u32x4 w; w.x = cvt_pk_bf16(v0[0], v0[1]); w.y = cvt_pk_bf16(v0[2], v0[3]); w.z = cvt_pk_bf16(v1[0], v1[1]); w.w = cvt_pk_bf16(v1[2], v1[3]);
;                         *(u32x4*)(MG + row * DM + col0 + bj * HALF) = w; } } }
.Lbr_zlast:
	global_load_dwordx4 v[144:147], v140, s[24:25] nt
	global_load_dwordx4 v[154:157], v140, s[24:25] offset:256 nt
	s_add_u32 s24, s24, 0x18000
	s_addc_u32 s25, s25, 0
	global_load_dwordx4 v[158:161], v140, s[24:25] nt
	global_load_dwordx4 v[162:165], v140, s[24:25] offset:256 nt
	s_add_u32 s24, s24, 0x18000
	s_addc_u32 s25, s25, 0
	global_load_dwordx4 v[166:169], v140, s[24:25] nt
	global_load_dwordx4 v[170:173], v140, s[24:25] offset:256 nt
	s_add_u32 s24, s24, 0x18000
	s_addc_u32 s25, s25, 0
	global_load_dwordx4 v[174:177], v140, s[24:25] nt
	global_load_dwordx4 v[178:181], v140, s[24:25] offset:256 nt
	s_add_u32 s24, s24, 0x78000
	s_addc_u32 s25, s25, 0
	global_load_dwordx4 v[182:185], v140, s[24:25] nt
	global_load_dwordx4 v[186:189], v140, s[24:25] offset:256 nt
	s_add_u32 s24, s24, 0x18000
	s_addc_u32 s25, s25, 0
	global_load_dwordx4 v[190:193], v140, s[24:25] nt
	global_load_dwordx4 v[194:197], v140, s[24:25] offset:256 nt
	s_add_u32 s24, s24, 0x18000
	s_addc_u32 s25, s25, 0
	global_load_dwordx4 v[198:201], v140, s[24:25] nt
	s_waitcnt vmcnt(12)
	v_lshlrev_b32_e32 v148, 16, v144
	v_and_b32_e32 v149, 0xffff0000, v144
	v_lshlrev_b32_e32 v210, 16, v146
	v_and_b32_e32 v211, 0xffff0000, v146
	v_lshlrev_b32_e32 v144, 16, v145
	v_and_b32_e32 v145, 0xffff0000, v145
	v_lshlrev_b32_e32 v146, 16, v147
	v_and_b32_e32 v147, 0xffff0000, v147
	v_pk_mul_f32 v[126:127], v[126:127], v[148:149]
	v_pk_mul_f32 v[128:129], v[128:129], v[144:145]
	v_pk_mul_f32 v[122:123], v[122:123], v[210:211]
	v_pk_mul_f32 v[124:125], v[124:125], v[146:147]
	v_cvt_pk_bf16_f32 v144, v126, v127
	v_cvt_pk_bf16_f32 v145, v128, v129
	v_cvt_pk_bf16_f32 v146, v122, v123
	v_cvt_pk_bf16_f32 v147, v124, v125
	global_store_dwordx4 v142, v[144:147], s[22:23]
	global_load_dwordx4 v[202:205], v140, s[24:25] offset:256 nt
	s_add_u32 s24, s24, 0x18000
	s_addc_u32 s25, s25, 0
	s_waitcnt vmcnt(13)
	v_lshlrev_b32_e32 v148, 16, v154
	v_and_b32_e32 v149, 0xffff0000, v154
	v_lshlrev_b32_e32 v210, 16, v156
	v_and_b32_e32 v211, 0xffff0000, v156
	v_lshlrev_b32_e32 v154, 16, v155
	v_and_b32_e32 v155, 0xffff0000, v155
	v_lshlrev_b32_e32 v156, 16, v157
	v_and_b32_e32 v157, 0xffff0000, v157
	v_pk_mul_f32 v[118:119], v[118:119], v[148:149]
	v_pk_mul_f32 v[120:121], v[120:121], v[154:155]
	v_pk_mul_f32 v[114:115], v[114:115], v[210:211]
	v_pk_mul_f32 v[116:117], v[116:117], v[156:157]
	v_cvt_pk_bf16_f32 v154, v118, v119
	v_cvt_pk_bf16_f32 v155, v120, v121
	v_cvt_pk_bf16_f32 v156, v114, v115
	v_cvt_pk_bf16_f32 v157, v116, v117
	global_store_dwordx4 v142, v[154:157], s[22:23] offset:256
	s_add_u32 s22, s22, 0x8000
	s_addc_u32 s23, s23, 0
	global_load_dwordx4 v[206:209], v140, s[24:25] nt
	s_waitcnt vmcnt(14)
	v_lshlrev_b32_e32 v148, 16, v158
	v_and_b32_e32 v149, 0xffff0000, v158
	v_lshlrev_b32_e32 v210, 16, v160
	v_and_b32_e32 v211, 0xffff0000, v160
	v_lshlrev_b32_e32 v158, 16, v159
	v_and_b32_e32 v159, 0xffff0000, v159
	v_lshlrev_b32_e32 v160, 16, v161
	v_and_b32_e32 v161, 0xffff0000, v161
	v_pk_mul_f32 v[110:111], v[110:111], v[148:149]
	v_pk_mul_f32 v[112:113], v[112:113], v[158:159]
	v_pk_mul_f32 v[106:107], v[106:107], v[210:211]
	v_pk_mul_f32 v[108:109], v[108:109], v[160:161]
	v_cvt_pk_bf16_f32 v158, v110, v111
	v_cvt_pk_bf16_f32 v159, v112, v113
	v_cvt_pk_bf16_f32 v160, v106, v107
	v_cvt_pk_bf16_f32 v161, v108, v109
	global_store_dwordx4 v142, v[158:161], s[22:23]
	global_load_dwordx4 v[126:129], v140, s[24:25] offset:256 nt
	s_waitcnt vmcnt(15)
	v_lshlrev_b32_e32 v148, 16, v162
	v_and_b32_e32 v149, 0xffff0000, v162
	v_lshlrev_b32_e32 v210, 16, v164
	v_and_b32_e32 v211, 0xffff0000, v164
	v_lshlrev_b32_e32 v162, 16, v163
	v_and_b32_e32 v163, 0xffff0000, v163
	v_lshlrev_b32_e32 v164, 16, v165
	v_and_b32_e32 v165, 0xffff0000, v165
	v_pk_mul_f32 v[102:103], v[102:103], v[148:149]
	v_pk_mul_f32 v[104:105], v[104:105], v[162:163]
	v_pk_mul_f32 v[98:99], v[98:99], v[210:211]
	v_pk_mul_f32 v[100:101], v[100:101], v[164:165]
	v_cvt_pk_bf16_f32 v162, v102, v103
	v_cvt_pk_bf16_f32 v163, v104, v105
	v_cvt_pk_bf16_f32 v164, v98, v99
	v_cvt_pk_bf16_f32 v165, v100, v101
	global_store_dwordx4 v142, v[162:165], s[22:23] offset:256
	s_add_u32 s22, s22, 0x8000
	s_addc_u32 s23, s23, 0
	s_waitcnt vmcnt(15)
	v_lshlrev_b32_e32 v148, 16, v166
	v_and_b32_e32 v149, 0xffff0000, v166
	v_lshlrev_b32_e32 v210, 16, v168
	v_and_b32_e32 v211, 0xffff0000, v168
	v_lshlrev_b32_e32 v166, 16, v167
	v_and_b32_e32 v167, 0xffff0000, v167
	v_lshlrev_b32_e32 v168, 16, v169
	v_and_b32_e32 v169, 0xffff0000, v169
	v_pk_mul_f32 v[94:95], v[94:95], v[148:149]
	v_pk_mul_f32 v[96:97], v[96:97], v[166:167]
	v_pk_mul_f32 v[90:91], v[90:91], v[210:211]
	v_pk_mul_f32 v[92:93], v[92:93], v[168:169]
	v_cvt_pk_bf16_f32 v166, v94, v95
	v_cvt_pk_bf16_f32 v167, v96, v97
	v_cvt_pk_bf16_f32 v168, v90, v91
	v_cvt_pk_bf16_f32 v169, v92, v93
	global_store_dwordx4 v142, v[166:169], s[22:23]
	s_waitcnt vmcnt(15)
	v_lshlrev_b32_e32 v148, 16, v170
	v_and_b32_e32 v149, 0xffff0000, v170
	v_lshlrev_b32_e32 v210, 16, v172
	v_and_b32_e32 v211, 0xffff0000, v172
	v_lshlrev_b32_e32 v170, 16, v171
	v_and_b32_e32 v171, 0xffff0000, v171
	v_lshlrev_b32_e32 v172, 16, v173
	v_and_b32_e32 v173, 0xffff0000, v173
	v_pk_mul_f32 v[86:87], v[86:87], v[148:149]
	v_pk_mul_f32 v[88:89], v[88:89], v[170:171]
	v_pk_mul_f32 v[82:83], v[82:83], v[210:211]
	v_pk_mul_f32 v[84:85], v[84:85], v[172:173]
	v_cvt_pk_bf16_f32 v170, v86, v87
	v_cvt_pk_bf16_f32 v171, v88, v89
	v_cvt_pk_bf16_f32 v172, v82, v83
	v_cvt_pk_bf16_f32 v173, v84, v85
	global_store_dwordx4 v142, v[170:173], s[22:23] offset:256
	s_add_u32 s22, s22, 0x8000
	s_addc_u32 s23, s23, 0
	s_waitcnt vmcnt(15)
; __device__ __forceinline__ unsigned cvt_pk_bf16(float lo, float hi) { f32x2 v = {lo, hi}; bf16x2_t b = __builtin_convertvector(v, bf16x2_t); return __builtin_bit_cast(unsigned, b); }
; __device__ __forceinline__ float bf_lo(unsigned w) { return __uint_as_float(w << 16); }
; __device__ __forceinline__ float bf_hi(unsigned w) { return __uint_as_float(w & 0xffff0000u); }
;     __device__ __forceinline__ void operator()(ACC_T, const Unit& u, int wr, int wc, int fr, int fq) const {
;     ...
;                     f32x4 v0 = acc[ai][bj][m][0], v1 = acc[ai][bj][m][1];
;                     v0[0] *= bf_lo(gw.x); v0[1] *= bf_hi(gw.x); v0[2] *= bf_lo(gw.y); v0[3] *= bf_hi(gw.y);
;                     v1[0] *= bf_lo(gw.z); v1[1] *= bf_hi(gw.z); v1[2] *= bf_lo(gw.w); v1[3] *= bf_hi(gw.w);
;                     float* mp = M32 + (size_t)u.pm * (SLOTB / 4) + (row - (size_t)u.pm * BM) * DM + col0 + bj * HALF;
;                     if (u.z > 0) { v0 += *(const f32x4*)mp; v1 += *(const f32x4*)(mp + 4); }
;                     if (u.z < 2) { *(f32x4*)mp = v0; *(f32x4*)(mp + 4) = v1; }
;                     else { u32x4 w; w.x = cvt_pk_bf16(v0[0], v0[1]); w.y = cvt_pk_bf16(v0[2], v0[3]); w.z = cvt_pk_bf16(v1[0], v1[1]); w.w = cvt_pk_bf16(v1[2], v1[3]);
;                         *(u32x4*)(MG + row * DM + col0 + bj * HALF) = w; } } }
	v_lshlrev_b32_e32 v148, 16, v174
	v_and_b32_e32 v149, 0xffff0000, v174
	v_lshlrev_b32_e32 v210, 16, v176
	v_and_b32_e32 v211, 0xffff0000, v176
	v_lshlrev_b32_e32 v174, 16, v175
	v_and_b32_e32 v175, 0xffff0000, v175
	v_lshlrev_b32_e32 v176, 16, v177
	v_and_b32_e32 v177, 0xffff0000, v177
	v_pk_mul_f32 v[78:79], v[78:79], v[148:149]
	v_pk_mul_f32 v[80:81], v[80:81], v[174:175]
	v_pk_mul_f32 v[74:75], v[74:75], v[210:211]
	v_pk_mul_f32 v[76:77], v[76:77], v[176:177]
	v_cvt_pk_bf16_f32 v174, v78, v79
	v_cvt_pk_bf16_f32 v175, v80, v81
	v_cvt_pk_bf16_f32 v176, v74, v75
	v_cvt_pk_bf16_f32 v177, v76, v77
	global_store_dwordx4 v142, v[174:177], s[22:23]
	s_waitcnt vmcnt(15)
	v_lshlrev_b32_e32 v148, 16, v178
	v_and_b32_e32 v149, 0xffff0000, v178
	v_lshlrev_b32_e32 v210, 16, v180
	v_and_b32_e32 v211, 0xffff0000, v180
	v_lshlrev_b32_e32 v178, 16, v179
	v_and_b32_e32 v179, 0xffff0000, v179
	v_lshlrev_b32_e32 v180, 16, v181
	v_and_b32_e32 v181, 0xffff0000, v181
	v_pk_mul_f32 v[70:71], v[70:71], v[148:149]
	v_pk_mul_f32 v[72:73], v[72:73], v[178:179]
	v_pk_mul_f32 v[66:67], v[66:67], v[210:211]
	v_pk_mul_f32 v[68:69], v[68:69], v[180:181]
	v_cvt_pk_bf16_f32 v178, v70, v71
	v_cvt_pk_bf16_f32 v179, v72, v73
	v_cvt_pk_bf16_f32 v180, v66, v67
	v_cvt_pk_bf16_f32 v181, v68, v69
	global_store_dwordx4 v142, v[178:181], s[22:23] offset:256
	s_add_u32 s22, s22, 0x28000
	s_addc_u32 s23, s23, 0
	s_waitcnt vmcnt(15)
	v_lshlrev_b32_e32 v148, 16, v182
	v_and_b32_e32 v149, 0xffff0000, v182
	v_lshlrev_b32_e32 v210, 16, v184
	v_and_b32_e32 v211, 0xffff0000, v184
	v_lshlrev_b32_e32 v182, 16, v183
	v_and_b32_e32 v183, 0xffff0000, v183
	v_lshlrev_b32_e32 v184, 16, v185
	v_and_b32_e32 v185, 0xffff0000, v185
	v_pk_mul_f32 v[62:63], v[62:63], v[148:149]
	v_pk_mul_f32 v[64:65], v[64:65], v[182:183]
	v_pk_mul_f32 v[58:59], v[58:59], v[210:211]
	v_pk_mul_f32 v[60:61], v[60:61], v[184:185]
	v_cvt_pk_bf16_f32 v182, v62, v63
	v_cvt_pk_bf16_f32 v183, v64, v65
	v_cvt_pk_bf16_f32 v184, v58, v59
	v_cvt_pk_bf16_f32 v185, v60, v61
	global_store_dwordx4 v142, v[182:185], s[22:23]
	s_waitcnt vmcnt(15)
	v_lshlrev_b32_e32 v148, 16, v186
	v_and_b32_e32 v149, 0xffff0000, v186
	v_lshlrev_b32_e32 v210, 16, v188
	v_and_b32_e32 v211, 0xffff0000, v188
	v_lshlrev_b32_e32 v186, 16, v187
	v_and_b32_e32 v187, 0xffff0000, v187
	v_lshlrev_b32_e32 v188, 16, v189
	v_and_b32_e32 v189, 0xffff0000, v189
	v_pk_mul_f32 v[54:55], v[54:55], v[148:149]
	v_pk_mul_f32 v[56:57], v[56:57], v[186:187]
	v_pk_mul_f32 v[50:51], v[50:51], v[210:211]
	v_pk_mul_f32 v[52:53], v[52:53], v[188:189]
	v_cvt_pk_bf16_f32 v186, v54, v55
	v_cvt_pk_bf16_f32 v187, v56, v57
	v_cvt_pk_bf16_f32 v188, v50, v51
	v_cvt_pk_bf16_f32 v189, v52, v53
	global_store_dwordx4 v142, v[186:189], s[22:23] offset:256
	s_add_u32 s22, s22, 0x8000
	s_addc_u32 s23, s23, 0
	s_waitcnt vmcnt(15)
	v_lshlrev_b32_e32 v148, 16, v190
	v_and_b32_e32 v149, 0xffff0000, v190
	v_lshlrev_b32_e32 v210, 16, v192
	v_and_b32_e32 v211, 0xffff0000, v192
	v_lshlrev_b32_e32 v190, 16, v191
	v_and_b32_e32 v191, 0xffff0000, v191
	v_lshlrev_b32_e32 v192, 16, v193
	v_and_b32_e32 v193, 0xffff0000, v193
	v_pk_mul_f32 v[46:47], v[46:47], v[148:149]
	v_pk_mul_f32 v[48:49], v[48:49], v[190:191]
	v_pk_mul_f32 v[42:43], v[42:43], v[210:211]
	v_pk_mul_f32 v[44:45], v[44:45], v[192:193]
	v_cvt_pk_bf16_f32 v190, v46, v47
	v_cvt_pk_bf16_f32 v191, v48, v49
	v_cvt_pk_bf16_f32 v192, v42, v43
	v_cvt_pk_bf16_f32 v193, v44, v45
	global_store_dwordx4 v142, v[190:193], s[22:23]
	s_waitcnt vmcnt(15)
	v_lshlrev_b32_e32 v148, 16, v194
	v_and_b32_e32 v149, 0xffff0000, v194
	v_lshlrev_b32_e32 v210, 16, v196
	v_and_b32_e32 v211, 0xffff0000, v196
	v_lshlrev_b32_e32 v194, 16, v195
	v_and_b32_e32 v195, 0xffff0000, v195
	v_lshlrev_b32_e32 v196, 16, v197
	v_and_b32_e32 v197, 0xffff0000, v197
	v_pk_mul_f32 v[38:39], v[38:39], v[148:149]
	v_pk_mul_f32 v[40:41], v[40:41], v[194:195]
	v_pk_mul_f32 v[34:35], v[34:35], v[210:211]
	v_pk_mul_f32 v[36:37], v[36:37], v[196:197]
	v_cvt_pk_bf16_f32 v194, v38, v39
	v_cvt_pk_bf16_f32 v195, v40, v41
	v_cvt_pk_bf16_f32 v196, v34, v35
	v_cvt_pk_bf16_f32 v197, v36, v37
	global_store_dwordx4 v142, v[194:197], s[22:23] offset:256
	s_add_u32 s22, s22, 0x8000
	s_addc_u32 s23, s23, 0
	s_waitcnt vmcnt(15)
	v_lshlrev_b32_e32 v148, 16, v198
	v_and_b32_e32 v149, 0xffff0000, v198
	v_lshlrev_b32_e32 v210, 16, v200
	v_and_b32_e32 v211, 0xffff0000, v200
	v_lshlrev_b32_e32 v198, 16, v199
	v_and_b32_e32 v199, 0xffff0000, v199
	v_lshlrev_b32_e32 v200, 16, v201
	v_and_b32_e32 v201, 0xffff0000, v201
	v_pk_mul_f32 v[30:31], v[30:31], v[148:149]
	v_pk_mul_f32 v[32:33], v[32:33], v[198:199]
	v_pk_mul_f32 v[26:27], v[26:27], v[210:211]
	v_pk_mul_f32 v[28:29], v[28:29], v[200:201]
	v_cvt_pk_bf16_f32 v198, v30, v31
	v_cvt_pk_bf16_f32 v199, v32, v33
	v_cvt_pk_bf16_f32 v200, v26, v27
	v_cvt_pk_bf16_f32 v201, v28, v29
	global_store_dwordx4 v142, v[198:201], s[22:23]
	s_waitcnt vmcnt(14)
	v_lshlrev_b32_e32 v148, 16, v202
	v_and_b32_e32 v149, 0xffff0000, v202
	v_lshlrev_b32_e32 v210, 16, v204
	v_and_b32_e32 v211, 0xffff0000, v204
	v_lshlrev_b32_e32 v202, 16, v203
	v_and_b32_e32 v203, 0xffff0000, v203
	v_lshlrev_b32_e32 v204, 16, v205
	v_and_b32_e32 v205, 0xffff0000, v205
	v_pk_mul_f32 v[22:23], v[22:23], v[148:149]
	v_pk_mul_f32 v[24:25], v[24:25], v[202:203]
	v_pk_mul_f32 v[18:19], v[18:19], v[210:211]
	v_pk_mul_f32 v[20:21], v[20:21], v[204:205]
	v_cvt_pk_bf16_f32 v202, v22, v23
	v_cvt_pk_bf16_f32 v203, v24, v25
	v_cvt_pk_bf16_f32 v204, v18, v19
	v_cvt_pk_bf16_f32 v205, v20, v21
	global_store_dwordx4 v142, v[202:205], s[22:23] offset:256
	s_add_u32 s22, s22, 0x8000
	s_addc_u32 s23, s23, 0
	s_waitcnt vmcnt(13)
	v_lshlrev_b32_e32 v148, 16, v206
	v_and_b32_e32 v149, 0xffff0000, v206
	v_lshlrev_b32_e32 v210, 16, v208
	v_and_b32_e32 v211, 0xffff0000, v208
	v_lshlrev_b32_e32 v206, 16, v207
	v_and_b32_e32 v207, 0xffff0000, v207
	v_lshlrev_b32_e32 v208, 16, v209
	v_and_b32_e32 v209, 0xffff0000, v209
	v_pk_mul_f32 v[14:15], v[14:15], v[148:149]
	v_pk_mul_f32 v[16:17], v[16:17], v[206:207]
	v_pk_mul_f32 v[10:11], v[10:11], v[210:211]
	v_pk_mul_f32 v[12:13], v[12:13], v[208:209]
	v_cvt_pk_bf16_f32 v206, v14, v15
	v_cvt_pk_bf16_f32 v207, v16, v17
	v_cvt_pk_bf16_f32 v208, v10, v11
	v_cvt_pk_bf16_f32 v209, v12, v13
	global_store_dwordx4 v142, v[206:209], s[22:23]
	s_waitcnt vmcnt(12)
	v_lshlrev_b32_e32 v148, 16, v126
	v_and_b32_e32 v149, 0xffff0000, v126
	v_lshlrev_b32_e32 v210, 16, v128
	v_and_b32_e32 v211, 0xffff0000, v128
	v_lshlrev_b32_e32 v126, 16, v127
	v_and_b32_e32 v127, 0xffff0000, v127
	v_lshlrev_b32_e32 v128, 16, v129
	v_and_b32_e32 v129, 0xffff0000, v129
	v_pk_mul_f32 v[6:7], v[6:7], v[148:149]
	v_pk_mul_f32 v[8:9], v[8:9], v[126:127]
	v_pk_mul_f32 v[2:3], v[2:3], v[210:211]
	v_pk_mul_f32 v[4:5], v[4:5], v[128:129]
	v_cvt_pk_bf16_f32 v126, v6, v7
	v_cvt_pk_bf16_f32 v127, v8, v9
	v_cvt_pk_bf16_f32 v128, v2, v3
	v_cvt_pk_bf16_f32 v129, v4, v5
	global_store_dwordx4 v142, v[126:129], s[22:23] offset:256
